# diff-attention unit prologue: the four norm-bound loads issued together (one round trip instead of four)
# speedup vs baseline: 1.0061x; 1.0061x over previous
; template <int MODE>
; DI void attn_unit(char* lds, const Params& p, int layer, int u) {
;     ...
;   if (MODE == 0) { h = u >> 8; b = (u >> 5) & 7; q0 = (u & 31) * 128; comp = wid >> 2; }
;   else if (MODE == 1 || MODE == 2) { h = (u >> 4) & 3; b = u >> 6; q0 = (u & 15) * 256; }
;   else { br = u >> 9; const int r = u & 511; b = r >> 6; h = (r >> 4) & 3; const int xx = r & 15; dl = 1 << (2 * br); rho = xx & (dl - 1); q0 = (xx >> (2 * br)) * 256; L = SEQ >> (2 * br); }
;   const int qrow = (MODE == 0) ? q0 + (wid & 3) * 32 + lr : q0 + wid * 32 + lr;
;   const int token = (MODE == 3) ? b * SEQ + rho + dl * qrow : b * SEQ + qrow;
;   int NT = (MODE == 3) ? 6 : 64, tlo = 0;
;   if (MODE == 0) {
;     const float sl2 = exp2f(-(float)(2 * h + 1)) * LOG2E;
;     const unsigned* km = p.nmax + ((b * 4 + h) * 2) * 64; const unsigned* qm = p.nmax + 4096 + ((b * 4 + h) * 2) * 32 + (q0 >> 7);
;     const float q0n = 1.02f * sqrtf(__uint_as_float(qm[0])), q1n = 1.02f * sqrtf(__uint_as_float(qm[32]));
;     const int td = q0 >> 6;
;     const float kd0 = sqrtf(fmaxf(__uint_as_float(km[td]), __uint_as_float(km[td + 1]))), kd1 = sqrtf(fmaxf(__uint_as_float(km[64 + td]), __uint_as_float(km[64 + td + 1])));
;     const float thr0 = -q0n * kd0 - 40.f, thr1 = -q1n * kd1 - 40.f;
.LBB0_604:
	s_add_i32 s0, s96, 0x300
	s_sub_i32 s1, 0x7ff, s96
	s_cmpk_lt_i32 s96, 0x100
	s_cselect_b32 s0, s0, s1
	s_ashr_i32 s50, s0, 8
	s_bfe_u32 s97, s0, 0x30005
	s_lshl_b32 s0, s0, 7
	s_lshl_b32 s51, s50, 1
	s_and_b32 s4, s0, 0xf80
	s_or_b32 s0, s51, 1
	v_cvt_f32_i32_e32 v0, s0
	s_mov_b32 s0, 0x42fc0000
	v_readlane_b32 s52, v252, 0
	v_readlane_b32 s56, v252, 4
	v_cmp_lt_f32_e32 vcc, s0, v0
	s_and_b64 s[0:1], vcc, exec
	s_cselect_b32 s0, 0xffffffc0, 0
	v_cndmask_b32_e32 v1, 0, v169, vcc
	v_sub_f32_e32 v0, v1, v0
	v_exp_f32_e32 v0, v0
	v_readlane_b32 s66, v252, 14
	v_readlane_b32 s57, v252, 5
	v_readlane_b32 s67, v252, 15
	v_ldexp_f32 v1, v0, s0
	s_lshl_b32 s0, s97, 3
	s_add_i32 s51, s0, s51
	s_lshl_b32 s0, s51, 6
	s_ashr_i32 s1, s0, 31
	s_lshl_b64 s[0:1], s[0:1], 2
	s_add_u32 s66, s56, s0
	s_addc_u32 s67, s57, s1
	s_lshl_b32 s0, s51, 5
	s_ashr_i32 s1, s0, 31
	s_lshl_b64 s[0:1], s[0:1], 2
	v_readlane_b32 s36, v253, 23
	v_readlane_b32 s53, v252, 1
	s_add_u32 s52, s36, s0
	v_readlane_b32 s0, v253, 25
	s_addc_u32 s53, s0, s1
	s_lshr_b32 s0, s4, 5
	v_mov_b32_e32 v172, v206
	v_mov_b32_e32 v2, s0
	global_load_dword v0, v2, s[52:53]
	global_load_dword v239, v2, s[52:53] offset:128
	s_lshr_b32 s70, s4, 4
	v_mov_b32_e32 v240, s70
	s_nop 1
	global_load_dwordx2 v[242:243], v240, s[66:67]
	global_load_dwordx2 v[246:247], v240, s[66:67] offset:256
	s_lshr_b32 s51, s4, 6
	v_readlane_b32 s54, v252, 2
	v_readlane_b32 s55, v252, 3
	s_or_b32 s56, s51, 1
	s_mov_b32 s33, 0
	s_add_i32 s54, s4, 0xffffff81
	s_mov_b64 s[68:69], 0
	s_mov_b32 s55, s51
	v_readlane_b32 s58, v252, 6
	v_readlane_b32 s59, v252, 7
	v_readlane_b32 s60, v252, 8
	v_readlane_b32 s61, v252, 9
	v_readlane_b32 s62, v252, 10
	v_readlane_b32 s63, v252, 11
	v_readlane_b32 s64, v252, 12
	v_readlane_b32 s65, v252, 13
	s_waitcnt vmcnt(0)
	v_cmp_gt_f32_e32 vcc, s75, v0
	v_mul_f32_e32 v3, 0x4f800000, v0
	s_nop 0
	v_cndmask_b32_e32 v0, v0, v3, vcc
	v_sqrt_f32_e32 v3, v0
	s_nop 0
	v_add_u32_e32 v4, -1, v3
	v_fma_f32 v5, -v4, v3, v0
	v_cmp_ge_f32_e64 s[0:1], 0, v5
	v_add_u32_e32 v5, 1, v3
	s_nop 0
	v_cndmask_b32_e64 v4, v3, v4, s[0:1]
	v_fma_f32 v3, -v5, v3, v0
	v_cmp_lt_f32_e64 s[0:1], 0, v3
	s_nop 1
	v_cndmask_b32_e64 v3, v4, v5, s[0:1]
	v_mul_f32_e32 v4, 0x37800000, v3
	v_cndmask_b32_e32 v3, v3, v4, vcc
	v_cmp_class_f32_e32 vcc, v0, v167
	s_nop 1
	v_cndmask_b32_e32 v0, v3, v0, vcc
	v_pk_mul_f32 v[118:119], v[0:1], s[10:11]
	v_mov_b32_e32 v0, v239
	s_xor_b32 s53, s4, 0xffffffc1
	s_mov_b32 s52, s56
	s_waitcnt vmcnt(0)
	v_cmp_gt_f32_e32 vcc, s75, v0
	v_mul_f32_e32 v1, 0x4f800000, v0
	s_nop 0
	v_cndmask_b32_e32 v0, v0, v1, vcc
	v_sqrt_f32_e32 v1, v0
	s_nop 0
	v_add_u32_e32 v2, -1, v1
	v_fma_f32 v3, -v2, v1, v0
	v_cmp_ge_f32_e64 s[0:1], 0, v3
	v_add_u32_e32 v3, 1, v1
	s_nop 0
	v_cndmask_b32_e64 v2, v1, v2, s[0:1]
	v_fma_f32 v1, -v3, v1, v0
	v_cmp_lt_f32_e64 s[0:1], 0, v1
	s_nop 1
	v_cndmask_b32_e64 v1, v2, v3, s[0:1]
	v_mul_f32_e32 v2, 0x37800000, v1
	v_cndmask_b32_e32 v1, v1, v2, vcc
	v_cmp_class_f32_e32 vcc, v0, v167
	s_lshr_b32 s0, s4, 4
	v_mov_b32_e32 v3, s0
	v_cndmask_b32_e32 v0, v1, v0, vcc
	v_mul_f32_e32 v2, 0x3f828f5c, v0
	v_mov_b64_e32 v[0:1], v[242:243]
	s_waitcnt vmcnt(0)
	v_max_f32_e32 v1, v1, v1
	v_max_f32_e32 v0, v0, v0
	v_max_f32_e32 v0, v0, v1
	v_cmp_gt_f32_e32 vcc, s75, v0
	v_mul_f32_e32 v1, 0x4f800000, v0
	s_nop 0
	v_cndmask_b32_e32 v0, v0, v1, vcc
	v_sqrt_f32_e32 v1, v0
	s_nop 0
	v_add_u32_e32 v4, -1, v1
	v_fma_f32 v5, -v4, v1, v0
	v_cmp_ge_f32_e64 s[0:1], 0, v5
	v_add_u32_e32 v5, 1, v1
	s_nop 0
	v_cndmask_b32_e64 v4, v1, v4, s[0:1]
	v_fma_f32 v1, -v5, v1, v0
	v_cmp_lt_f32_e64 s[0:1], 0, v1
	s_nop 1
	v_cndmask_b32_e64 v1, v4, v5, s[0:1]
	v_mul_f32_e32 v4, 0x37800000, v1
	v_cndmask_b32_e32 v1, v1, v4, vcc
	v_cmp_class_f32_e32 vcc, v0, v167
	s_nop 1
	v_cndmask_b32_e32 v4, v1, v0, vcc
	v_mov_b64_e32 v[0:1], v[246:247]
	s_waitcnt vmcnt(0)
	v_max_f32_e32 v1, v1, v1
	v_max_f32_e32 v0, v0, v0
	v_max_f32_e32 v0, v0, v1
	v_cmp_gt_f32_e32 vcc, s75, v0
	v_mul_f32_e32 v1, 0x4f800000, v0
	s_nop 0
	v_cndmask_b32_e32 v0, v0, v1, vcc
	v_sqrt_f32_e32 v1, v0
	s_nop 0
	v_add_u32_e32 v3, -1, v1
	v_fma_f32 v5, -v3, v1, v0
	v_cmp_ge_f32_e64 s[0:1], 0, v5
	v_add_u32_e32 v5, 1, v1
	s_nop 0
	v_cndmask_b32_e64 v3, v1, v3, s[0:1]
	v_fma_f32 v1, -v5, v1, v0
	v_cmp_lt_f32_e64 s[0:1], 0, v1
	s_nop 1
	v_cndmask_b32_e64 v1, v3, v5, s[0:1]
	v_mul_f32_e32 v3, 0x37800000, v1
	v_cndmask_b32_e32 v1, v1, v3, vcc
	v_cmp_class_f32_e32 vcc, v0, v167
	v_fma_f32 v3, -v118, v4, s24
	s_nop 0
	v_cndmask_b32_e32 v0, v1, v0, vcc
	v_fma_f32 v4, -v2, v0, s24
	s_branch .LBB0_606

; template <int MODE>
; DI void attn_unit(char* lds, const Params& p, int layer, int u) {
;     ...
;   if (MODE == 0) { h = u >> 8; b = (u >> 5) & 7; q0 = (u & 31) * 128; comp = wid >> 2; }
;   else if (MODE == 1 || MODE == 2) { h = (u >> 4) & 3; b = u >> 6; q0 = (u & 15) * 256; }
;   else { br = u >> 9; const int r = u & 511; b = r >> 6; h = (r >> 4) & 3; const int xx = r & 15; dl = 1 << (2 * br); rho = xx & (dl - 1); q0 = (xx >> (2 * br)) * 256; L = SEQ >> (2 * br); }
;   const int qrow = (MODE == 0) ? q0 + (wid & 3) * 32 + lr : q0 + wid * 32 + lr;
;   const int token = (MODE == 3) ? b * SEQ + rho + dl * qrow : b * SEQ + qrow;
;   int NT = (MODE == 3) ? 6 : 64, tlo = 0;
;   if (MODE == 0) {
;     const float sl2 = exp2f(-(float)(2 * h + 1)) * LOG2E;
;     const unsigned* km = p.nmax + ((b * 4 + h) * 2) * 64; const unsigned* qm = p.nmax + 4096 + ((b * 4 + h) * 2) * 32 + (q0 >> 7);
;     const float q0n = 1.02f * sqrtf(__uint_as_float(qm[0])), q1n = 1.02f * sqrtf(__uint_as_float(qm[32]));
;     const int td = q0 >> 6;
;     const float kd0 = sqrtf(fmaxf(__uint_as_float(km[td]), __uint_as_float(km[td + 1]))), kd1 = sqrtf(fmaxf(__uint_as_float(km[64 + td]), __uint_as_float(km[64 + td + 1])));
;     const float thr0 = -q0n * kd0 - 40.f, thr1 = -q1n * kd1 - 40.f;
.LBB0_1581:
	s_add_i32 s0, s90, 0x300
	s_sub_i32 s1, 0x7ff, s90
	s_cmpk_lt_i32 s90, 0x100
	s_cselect_b32 s0, s0, s1
	s_ashr_i32 s96, s0, 8
	s_bfe_u32 s91, s0, 0x30005
	s_lshl_b32 s0, s0, 7
	s_lshl_b32 s50, s96, 1
	s_and_b32 s4, s0, 0xf80
	s_or_b32 s0, s50, 1
	v_cvt_f32_i32_e32 v0, s0
	s_mov_b32 s0, 0x42fc0000
	v_readlane_b32 s52, v252, 0
	v_readlane_b32 s56, v252, 4
	v_cmp_lt_f32_e32 vcc, s0, v0
	s_and_b64 s[0:1], vcc, exec
	s_cselect_b32 s0, 0xffffffc0, 0
	v_cndmask_b32_e32 v1, 0, v169, vcc
	v_sub_f32_e32 v0, v1, v0
	v_exp_f32_e32 v0, v0
	v_readlane_b32 s66, v252, 14
	v_readlane_b32 s57, v252, 5
	v_readlane_b32 s67, v252, 15
	v_ldexp_f32 v1, v0, s0
	s_lshl_b32 s0, s91, 3
	s_add_i32 s50, s0, s50
	s_lshl_b32 s0, s50, 6
	s_ashr_i32 s1, s0, 31
	s_lshl_b64 s[0:1], s[0:1], 2
	s_add_u32 s66, s56, s0
	s_addc_u32 s67, s57, s1
	s_lshl_b32 s0, s50, 5
	s_ashr_i32 s1, s0, 31
	s_lshl_b64 s[0:1], s[0:1], 2
	v_readlane_b32 s8, v253, 23
	s_add_u32 s50, s8, s0
	v_readlane_b32 s0, v253, 25
	s_addc_u32 s51, s0, s1
	s_lshr_b32 s0, s4, 5
	v_mov_b32_e32 v172, v206
	v_mov_b32_e32 v2, s0
	global_load_dword v0, v2, s[50:51]
	global_load_dword v239, v2, s[50:51] offset:128
	s_lshr_b32 s70, s4, 4
	v_mov_b32_e32 v240, s70
	s_nop 1
	global_load_dwordx2 v[242:243], v240, s[66:67]
	global_load_dwordx2 v[246:247], v240, s[66:67] offset:256
	v_readlane_b32 s54, v252, 2
	s_lshr_b32 s97, s4, 6
	v_readlane_b32 s53, v252, 1
	s_or_b32 s54, s97, 1
	s_mov_b32 s33, 0
	s_add_i32 s52, s4, 0xffffff81
	s_mov_b64 s[68:69], 0
	s_mov_b32 s53, s97
	v_readlane_b32 s55, v252, 3
	v_readlane_b32 s58, v252, 6
	v_readlane_b32 s59, v252, 7
	v_readlane_b32 s60, v252, 8
	v_readlane_b32 s61, v252, 9
	v_readlane_b32 s62, v252, 10
	v_readlane_b32 s63, v252, 11
	v_readlane_b32 s64, v252, 12
	v_readlane_b32 s65, v252, 13
	s_waitcnt vmcnt(0)
	v_cmp_gt_f32_e32 vcc, s75, v0
	v_mul_f32_e32 v3, 0x4f800000, v0
	s_nop 0
	v_cndmask_b32_e32 v0, v0, v3, vcc
	v_sqrt_f32_e32 v3, v0
	s_nop 0
	v_add_u32_e32 v4, -1, v3
	v_fma_f32 v5, -v4, v3, v0
	v_cmp_ge_f32_e64 s[0:1], 0, v5
	v_add_u32_e32 v5, 1, v3
	s_nop 0
	v_cndmask_b32_e64 v4, v3, v4, s[0:1]
	v_fma_f32 v3, -v5, v3, v0
	v_cmp_lt_f32_e64 s[0:1], 0, v3
	s_nop 1
	v_cndmask_b32_e64 v3, v4, v5, s[0:1]
	v_mul_f32_e32 v4, 0x37800000, v3
	v_cndmask_b32_e32 v3, v3, v4, vcc
	v_cmp_class_f32_e32 vcc, v0, v167
	s_nop 1
	v_cndmask_b32_e32 v0, v3, v0, vcc
	v_pk_mul_f32 v[118:119], v[0:1], s[28:29]
	v_mov_b32_e32 v0, v239
	s_xor_b32 s51, s4, 0xffffffc1
	s_mov_b32 s50, s54
	s_waitcnt vmcnt(0)
	v_cmp_gt_f32_e32 vcc, s75, v0
	v_mul_f32_e32 v1, 0x4f800000, v0
	s_nop 0
	v_cndmask_b32_e32 v0, v0, v1, vcc
	v_sqrt_f32_e32 v1, v0
	s_nop 0
	v_add_u32_e32 v2, -1, v1
	v_fma_f32 v3, -v2, v1, v0
	v_cmp_ge_f32_e64 s[0:1], 0, v3
	v_add_u32_e32 v3, 1, v1
	s_nop 0
	v_cndmask_b32_e64 v2, v1, v2, s[0:1]
	v_fma_f32 v1, -v3, v1, v0
	v_cmp_lt_f32_e64 s[0:1], 0, v1
	s_nop 1
	v_cndmask_b32_e64 v1, v2, v3, s[0:1]
	v_mul_f32_e32 v2, 0x37800000, v1
	v_cndmask_b32_e32 v1, v1, v2, vcc
	v_cmp_class_f32_e32 vcc, v0, v167
	s_lshr_b32 s0, s4, 4
	v_mov_b32_e32 v3, s0
	v_cndmask_b32_e32 v0, v1, v0, vcc
	v_mul_f32_e32 v2, 0x3f828f5c, v0
	v_mov_b64_e32 v[0:1], v[242:243]
	s_waitcnt vmcnt(0)
	v_max_f32_e32 v1, v1, v1
	v_max_f32_e32 v0, v0, v0
	v_max_f32_e32 v0, v0, v1
	v_cmp_gt_f32_e32 vcc, s75, v0
	v_mul_f32_e32 v1, 0x4f800000, v0
	s_nop 0
	v_cndmask_b32_e32 v0, v0, v1, vcc
	v_sqrt_f32_e32 v1, v0
	s_nop 0
	v_add_u32_e32 v4, -1, v1
	v_fma_f32 v5, -v4, v1, v0
	v_cmp_ge_f32_e64 s[0:1], 0, v5
	v_add_u32_e32 v5, 1, v1
	s_nop 0
	v_cndmask_b32_e64 v4, v1, v4, s[0:1]
	v_fma_f32 v1, -v5, v1, v0
	v_cmp_lt_f32_e64 s[0:1], 0, v1
	s_nop 1
	v_cndmask_b32_e64 v1, v4, v5, s[0:1]
	v_mul_f32_e32 v4, 0x37800000, v1
	v_cndmask_b32_e32 v1, v1, v4, vcc
	v_cmp_class_f32_e32 vcc, v0, v167
	s_nop 1
	v_cndmask_b32_e32 v4, v1, v0, vcc
	v_mov_b64_e32 v[0:1], v[246:247]
	s_waitcnt vmcnt(0)
	v_max_f32_e32 v1, v1, v1
	v_max_f32_e32 v0, v0, v0
	v_max_f32_e32 v0, v0, v1
	v_cmp_gt_f32_e32 vcc, s75, v0
	v_mul_f32_e32 v1, 0x4f800000, v0
	s_nop 0
	v_cndmask_b32_e32 v0, v0, v1, vcc
	v_sqrt_f32_e32 v1, v0
	s_nop 0
	v_add_u32_e32 v3, -1, v1
	v_fma_f32 v5, -v3, v1, v0
	v_cmp_ge_f32_e64 s[0:1], 0, v5
	v_add_u32_e32 v5, 1, v1
	s_nop 0
	v_cndmask_b32_e64 v3, v1, v3, s[0:1]
	v_fma_f32 v1, -v5, v1, v0
	v_cmp_lt_f32_e64 s[0:1], 0, v1
	s_nop 1
	v_cndmask_b32_e64 v1, v3, v5, s[0:1]
	v_mul_f32_e32 v3, 0x37800000, v1
	v_cndmask_b32_e32 v1, v1, v3, vcc
	v_cmp_class_f32_e32 vcc, v0, v167
	v_fma_f32 v3, -v118, v4, s76
	s_nop 0
	v_cndmask_b32_e32 v0, v1, v0, vcc
	v_fma_f32 v4, -v2, v0, s76
	s_branch .LBB0_1583
